# FFN-up epilogue: the 8 per-row ssq loads issued together at the start (one wait instead of 8 round trips)
# speedup vs baseline: 1.0143x; 1.0019x over previous
; __device__ __forceinline__ unsigned cvt_pk_bf16(float lo, float hi) { const cvt2_f32x2 v = {lo, hi}; const cvt2_bf16x2 r = __builtin_convertvector(v, cvt2_bf16x2); return __builtin_bit_cast(unsigned, r); }
;     __device__ __forceinline__ void operator()(const f32x4 (&acc)[2][2][4][2], const Unit& u, int wr, int wc, int fr, int fq) const {
;         const int row0 = u.pm * BM + wr * 64 + fr, col0 = u.pn * BM + wc * 32 + 8 * fq;
; #pragma unroll
;         for (int ai = 0; ai < 2; ++ai)
; #pragma unroll
;             for (int m = 0; m < 4; ++m) {
;                 const int row = row0 + ai * HALF + m * 16;
;                 const float rs = ssq ? rsqrtf(ssq[row] * (1.0f / 2048.0f) + RMS_EPS) : 1.0f;
;                 bf16_t* rowp = O + (size_t)row * ldc + col0;
; #pragma unroll
;                 for (int bj = 0; bj < 2; ++bj) {
;                     f32x4 v0 = acc[ai][bj][m][0] * rs, v1 = acc[ai][bj][m][1] * rs;
;                     if (RELU2) {
; #pragma unroll
;                         for (int e = 0; e < 4; ++e) { float a = fmaxf(v0[e], 0.f), b = fmaxf(v1[e], 0.f); v0[e] = a * a; v1[e] = b * b; }
;                     }
;                     u32x4 w; w.x = cvt_pk_bf16(v0[0], v0[1]); w.y = cvt_pk_bf16(v0[2], v0[3]); w.z = cvt_pk_bf16(v1[0], v1[1]); w.w = cvt_pk_bf16(v1[2], v1[3]);
;                     *(u32x4*)(rowp + bj * HALF) = w;
;                 }
.LBB0_418:
	v_lshl_add_u32 v140, s35, 8, v145
	v_cndmask_b32_e64 v142, 0, 1, s[18:19]
	v_ashrrev_i32_e32 v141, 31, v140
	v_mov_b32_e32 v144, 1.0
	v_cmp_ne_u32_e64 s[6:7], 1, v142
	s_andn2_b64 vcc, exec, s[18:19]
	v_mov_b32_e32 v146, 1.0
	s_mov_b32 s68, 0x60000
	s_mov_b32 s70, 0x20000
	s_mov_b32 s72, 0x24000
	s_cbranch_vccnz .LBB0_420
	v_lshl_add_u64 v[142:143], v[140:141], 2, s[10:11]
	global_load_dword v156, v[142:143], off offset:64
	global_load_dword v157, v[142:143], off offset:128
	global_load_dword v158, v[142:143], off offset:192
	global_load_dword v159, v[142:143], off offset:512
	global_load_dword v160, v[142:143], off offset:576
	global_load_dword v161, v[142:143], off offset:640
	global_load_dword v162, v[142:143], off offset:704
	global_load_dword v142, v[142:143], off
	s_waitcnt vmcnt(0)
	v_fmamk_f32 v142, v142, 0x3a000000, v198
	v_mul_f32_e32 v143, 0x4b800000, v142
	v_cmp_gt_f32_e32 vcc, s16, v142
	s_nop 1
	v_cndmask_b32_e32 v142, v142, v143, vcc
	v_rsq_f32_e32 v142, v142
	s_nop 0
	v_mul_f32_e32 v143, 0x45800000, v142
	v_cndmask_b32_e32 v146, v142, v143, vcc
.LBB0_420:
	v_pk_mul_f32 v[122:123], v[122:123], v[146:147] op_sel_hi:[1,0]
	v_pk_mul_f32 v[128:129], v[128:129], v[146:147] op_sel_hi:[1,0]
	v_pk_mul_f32 v[126:127], v[126:127], v[146:147] op_sel_hi:[1,0]
	v_pk_mul_f32 v[124:125], v[124:125], v[146:147] op_sel_hi:[1,0]
	v_max_f32_e32 v122, 0, v122
	v_max_f32_e32 v123, 0, v123
	v_lshl_or_b32 v142, s34, 8, v148
	v_lshlrev_b64 v[150:151], 14, v[140:141]
	v_max_f32_e32 v126, 0, v126
	v_max_f32_e32 v127, 0, v127
	v_pk_mul_f32 v[152:153], v[122:123], v[122:123]
	v_max_f32_e32 v122, 0, v128
	v_max_f32_e32 v124, 0, v124
	v_max_f32_e32 v123, 0, v129
	v_max_f32_e32 v125, 0, v125
	v_ashrrev_i32_e32 v143, 31, v142
	v_lshl_add_u64 v[150:151], s[30:31], 0, v[150:151]
	v_pk_mul_f32 v[126:127], v[126:127], v[126:127]
	v_pk_mul_f32 v[128:129], v[122:123], v[122:123]
	v_pk_mul_f32 v[154:155], v[124:125], v[124:125]
	v_pk_mul_f32 v[114:115], v[114:115], v[146:147] op_sel_hi:[1,0]
	v_lshl_add_u64 v[150:151], v[142:143], 1, v[150:151]
	v_cvt_pk_bf16_f32 v122, v126, v127
	v_cvt_pk_bf16_f32 v123, v128, v129
	v_cvt_pk_bf16_f32 v124, v152, v153
	v_cvt_pk_bf16_f32 v125, v154, v155
	v_pk_mul_f32 v[120:121], v[120:121], v[146:147] op_sel_hi:[1,0]
	v_pk_mul_f32 v[118:119], v[118:119], v[146:147] op_sel_hi:[1,0]
	v_pk_mul_f32 v[116:117], v[116:117], v[146:147] op_sel_hi:[1,0]
	v_max_f32_e32 v114, 0, v114
	v_max_f32_e32 v115, 0, v115
	global_store_dwordx4 v[150:151], v[122:125], off
	v_max_f32_e32 v118, 0, v118
	v_max_f32_e32 v119, 0, v119
	v_pk_mul_f32 v[122:123], v[114:115], v[114:115]
	v_max_f32_e32 v114, 0, v120
	v_max_f32_e32 v116, 0, v116
	v_max_f32_e32 v115, 0, v121
	v_max_f32_e32 v117, 0, v117
	v_pk_mul_f32 v[118:119], v[118:119], v[118:119]
	v_pk_mul_f32 v[120:121], v[114:115], v[114:115]
	v_pk_mul_f32 v[124:125], v[116:117], v[116:117]
	v_cvt_pk_bf16_f32 v114, v118, v119
	v_cvt_pk_bf16_f32 v115, v120, v121
	v_cvt_pk_bf16_f32 v116, v122, v123
	v_cvt_pk_bf16_f32 v117, v124, v125
	global_store_dwordx4 v[150:151], v[114:117], off offset:256
	s_and_b64 vcc, exec, s[6:7]
	s_nop 0
	v_or_b32_e32 v114, 16, v140
	v_ashrrev_i32_e32 v115, 31, v114
	s_cbranch_vccnz .LBB0_422
	v_mov_b32_e32 v116, v156
	v_fmamk_f32 v116, v116, 0x3a000000, v198
	v_mul_f32_e32 v117, 0x4b800000, v116
	v_cmp_gt_f32_e32 vcc, s16, v116
	s_nop 1
	v_cndmask_b32_e32 v116, v116, v117, vcc
	v_rsq_f32_e32 v116, v116
	s_nop 0
	v_mul_f32_e32 v117, 0x45800000, v116
	v_cndmask_b32_e32 v144, v116, v117, vcc
.LBB0_422:
	v_pk_mul_f32 v[106:107], v[106:107], v[144:145] op_sel_hi:[1,0]
	v_pk_mul_f32 v[112:113], v[112:113], v[144:145] op_sel_hi:[1,0]
	v_pk_mul_f32 v[110:111], v[110:111], v[144:145] op_sel_hi:[1,0]
	v_pk_mul_f32 v[108:109], v[108:109], v[144:145] op_sel_hi:[1,0]
	v_max_f32_e32 v106, 0, v106
	v_max_f32_e32 v107, 0, v107
	v_lshlrev_b64 v[114:115], 14, v[114:115]
	v_max_f32_e32 v110, 0, v110
	v_max_f32_e32 v111, 0, v111
	v_pk_mul_f32 v[116:117], v[106:107], v[106:107]
	v_max_f32_e32 v106, 0, v112
	v_max_f32_e32 v108, 0, v108
	v_max_f32_e32 v107, 0, v113
	v_max_f32_e32 v109, 0, v109
	v_lshl_add_u64 v[114:115], s[30:31], 0, v[114:115]
	v_pk_mul_f32 v[110:111], v[110:111], v[110:111]
	v_pk_mul_f32 v[112:113], v[106:107], v[106:107]
	v_pk_mul_f32 v[118:119], v[108:109], v[108:109]
	v_pk_mul_f32 v[98:99], v[98:99], v[144:145] op_sel_hi:[1,0]
	v_lshl_add_u64 v[114:115], v[142:143], 1, v[114:115]
	v_cvt_pk_bf16_f32 v106, v110, v111
	v_cvt_pk_bf16_f32 v107, v112, v113
	v_cvt_pk_bf16_f32 v108, v116, v117
	v_cvt_pk_bf16_f32 v109, v118, v119
	v_pk_mul_f32 v[104:105], v[104:105], v[144:145] op_sel_hi:[1,0]
	v_pk_mul_f32 v[102:103], v[102:103], v[144:145] op_sel_hi:[1,0]
	v_pk_mul_f32 v[100:101], v[100:101], v[144:145] op_sel_hi:[1,0]
	v_max_f32_e32 v98, 0, v98
	v_max_f32_e32 v99, 0, v99
	global_store_dwordx4 v[114:115], v[106:109], off
	v_max_f32_e32 v102, 0, v102
	v_max_f32_e32 v103, 0, v103
	v_pk_mul_f32 v[106:107], v[98:99], v[98:99]
	v_max_f32_e32 v98, 0, v104
	v_max_f32_e32 v100, 0, v100
	v_max_f32_e32 v99, 0, v105
	v_max_f32_e32 v101, 0, v101
	v_pk_mul_f32 v[102:103], v[102:103], v[102:103]
	v_pk_mul_f32 v[104:105], v[98:99], v[98:99]
	v_pk_mul_f32 v[108:109], v[100:101], v[100:101]
	v_cvt_pk_bf16_f32 v98, v102, v103
	v_cvt_pk_bf16_f32 v99, v104, v105
	v_cvt_pk_bf16_f32 v100, v106, v107
	v_cvt_pk_bf16_f32 v101, v108, v109
	v_or_b32_e32 v102, 32, v140
	global_store_dwordx4 v[114:115], v[98:101], off offset:256
	v_ashrrev_i32_e32 v103, 31, v102
	s_and_b64 vcc, exec, s[6:7]
	v_mov_b32_e32 v98, 1.0
	v_mov_b32_e32 v100, 1.0
	s_cbranch_vccnz .LBB0_424
	v_mov_b32_e32 v99, v157
	v_fmamk_f32 v99, v99, 0x3a000000, v198
	v_mul_f32_e32 v100, 0x4b800000, v99
	v_cmp_gt_f32_e32 vcc, s16, v99
	s_nop 1
	v_cndmask_b32_e32 v99, v99, v100, vcc
	v_rsq_f32_e32 v99, v99
	s_nop 0
	v_mul_f32_e32 v100, 0x45800000, v99
	v_cndmask_b32_e32 v100, v99, v100, vcc
; __device__ __forceinline__ unsigned cvt_pk_bf16(float lo, float hi) { const cvt2_f32x2 v = {lo, hi}; const cvt2_bf16x2 r = __builtin_convertvector(v, cvt2_bf16x2); return __builtin_bit_cast(unsigned, r); }
;     __device__ __forceinline__ void operator()(const f32x4 (&acc)[2][2][4][2], const Unit& u, int wr, int wc, int fr, int fq) const {
;         const int row0 = u.pm * BM + wr * 64 + fr, col0 = u.pn * BM + wc * 32 + 8 * fq;
; #pragma unroll
;         for (int ai = 0; ai < 2; ++ai)
; #pragma unroll
;             for (int m = 0; m < 4; ++m) {
;                 const int row = row0 + ai * HALF + m * 16;
;                 const float rs = ssq ? rsqrtf(ssq[row] * (1.0f / 2048.0f) + RMS_EPS) : 1.0f;
;                 bf16_t* rowp = O + (size_t)row * ldc + col0;
; #pragma unroll
;                 for (int bj = 0; bj < 2; ++bj) {
;                     f32x4 v0 = acc[ai][bj][m][0] * rs, v1 = acc[ai][bj][m][1] * rs;
;                     if (RELU2) {
; #pragma unroll
;                         for (int e = 0; e < 4; ++e) { float a = fmaxf(v0[e], 0.f), b = fmaxf(v1[e], 0.f); v0[e] = a * a; v1[e] = b * b; }
;                     }
;                     u32x4 w; w.x = cvt_pk_bf16(v0[0], v0[1]); w.y = cvt_pk_bf16(v0[2], v0[3]); w.z = cvt_pk_bf16(v1[0], v1[1]); w.w = cvt_pk_bf16(v1[2], v1[3]);
;                     *(u32x4*)(rowp + bj * HALF) = w;
;                 }
.LBB0_424:
	v_pk_mul_f32 v[90:91], v[90:91], v[100:101] op_sel_hi:[1,0]
	v_pk_mul_f32 v[96:97], v[96:97], v[100:101] op_sel_hi:[1,0]
	v_pk_mul_f32 v[94:95], v[94:95], v[100:101] op_sel_hi:[1,0]
	v_pk_mul_f32 v[92:93], v[92:93], v[100:101] op_sel_hi:[1,0]
	v_max_f32_e32 v90, 0, v90
	v_max_f32_e32 v91, 0, v91
	v_lshlrev_b64 v[102:103], 14, v[102:103]
	v_max_f32_e32 v94, 0, v94
	v_max_f32_e32 v95, 0, v95
	v_pk_mul_f32 v[104:105], v[90:91], v[90:91]
	v_max_f32_e32 v90, 0, v96
	v_max_f32_e32 v92, 0, v92
	v_max_f32_e32 v91, 0, v97
	v_max_f32_e32 v93, 0, v93
	v_lshl_add_u64 v[102:103], s[30:31], 0, v[102:103]
	v_pk_mul_f32 v[94:95], v[94:95], v[94:95]
	v_pk_mul_f32 v[96:97], v[90:91], v[90:91]
	v_pk_mul_f32 v[106:107], v[92:93], v[92:93]
	v_pk_mul_f32 v[82:83], v[82:83], v[100:101] op_sel_hi:[1,0]
	v_lshl_add_u64 v[102:103], v[142:143], 1, v[102:103]
	v_cvt_pk_bf16_f32 v90, v94, v95
	v_cvt_pk_bf16_f32 v91, v96, v97
	v_cvt_pk_bf16_f32 v92, v104, v105
	v_cvt_pk_bf16_f32 v93, v106, v107
	v_pk_mul_f32 v[88:89], v[88:89], v[100:101] op_sel_hi:[1,0]
	v_pk_mul_f32 v[86:87], v[86:87], v[100:101] op_sel_hi:[1,0]
	v_pk_mul_f32 v[84:85], v[84:85], v[100:101] op_sel_hi:[1,0]
	v_max_f32_e32 v82, 0, v82
	v_max_f32_e32 v83, 0, v83
	global_store_dwordx4 v[102:103], v[90:93], off
	v_max_f32_e32 v86, 0, v86
	v_max_f32_e32 v87, 0, v87
	v_pk_mul_f32 v[90:91], v[82:83], v[82:83]
	v_max_f32_e32 v82, 0, v88
	v_max_f32_e32 v84, 0, v84
	v_max_f32_e32 v83, 0, v89
	v_max_f32_e32 v85, 0, v85
	v_pk_mul_f32 v[86:87], v[86:87], v[86:87]
	v_pk_mul_f32 v[88:89], v[82:83], v[82:83]
	v_pk_mul_f32 v[92:93], v[84:85], v[84:85]
	v_cvt_pk_bf16_f32 v82, v86, v87
	v_cvt_pk_bf16_f32 v83, v88, v89
	v_cvt_pk_bf16_f32 v84, v90, v91
	v_cvt_pk_bf16_f32 v85, v92, v93
	global_store_dwordx4 v[102:103], v[82:85], off offset:256
	s_and_b64 vcc, exec, s[6:7]
	s_nop 0
	v_or_b32_e32 v82, 48, v140
	v_ashrrev_i32_e32 v83, 31, v82
	s_cbranch_vccnz .LBB0_426
	v_mov_b32_e32 v84, v158
	v_fmamk_f32 v84, v84, 0x3a000000, v198
	v_mul_f32_e32 v85, 0x4b800000, v84
	v_cmp_gt_f32_e32 vcc, s16, v84
	s_nop 1
	v_cndmask_b32_e32 v84, v84, v85, vcc
	v_rsq_f32_e32 v84, v84
	s_nop 0
	v_mul_f32_e32 v85, 0x45800000, v84
	v_cndmask_b32_e32 v98, v84, v85, vcc
.LBB0_426:
	v_pk_mul_f32 v[74:75], v[74:75], v[98:99] op_sel_hi:[1,0]
	v_pk_mul_f32 v[80:81], v[80:81], v[98:99] op_sel_hi:[1,0]
	v_pk_mul_f32 v[78:79], v[78:79], v[98:99] op_sel_hi:[1,0]
	v_pk_mul_f32 v[76:77], v[76:77], v[98:99] op_sel_hi:[1,0]
	v_max_f32_e32 v74, 0, v74
	v_max_f32_e32 v75, 0, v75
	v_lshlrev_b64 v[82:83], 14, v[82:83]
	v_max_f32_e32 v78, 0, v78
	v_max_f32_e32 v79, 0, v79
	v_pk_mul_f32 v[84:85], v[74:75], v[74:75]
	v_max_f32_e32 v74, 0, v80
	v_max_f32_e32 v76, 0, v76
	v_max_f32_e32 v75, 0, v81
	v_max_f32_e32 v77, 0, v77
	v_lshl_add_u64 v[82:83], s[30:31], 0, v[82:83]
	v_pk_mul_f32 v[78:79], v[78:79], v[78:79]
	v_pk_mul_f32 v[80:81], v[74:75], v[74:75]
	v_pk_mul_f32 v[86:87], v[76:77], v[76:77]
	v_pk_mul_f32 v[66:67], v[66:67], v[98:99] op_sel_hi:[1,0]
	v_lshl_add_u64 v[82:83], v[142:143], 1, v[82:83]
	v_cvt_pk_bf16_f32 v74, v78, v79
	v_cvt_pk_bf16_f32 v75, v80, v81
	v_cvt_pk_bf16_f32 v76, v84, v85
	v_cvt_pk_bf16_f32 v77, v86, v87
	v_pk_mul_f32 v[72:73], v[72:73], v[98:99] op_sel_hi:[1,0]
	v_pk_mul_f32 v[70:71], v[70:71], v[98:99] op_sel_hi:[1,0]
	v_pk_mul_f32 v[68:69], v[68:69], v[98:99] op_sel_hi:[1,0]
	v_max_f32_e32 v66, 0, v66
	v_max_f32_e32 v67, 0, v67
	global_store_dwordx4 v[82:83], v[74:77], off
	v_max_f32_e32 v70, 0, v70
	v_max_f32_e32 v71, 0, v71
	v_pk_mul_f32 v[74:75], v[66:67], v[66:67]
	v_max_f32_e32 v66, 0, v72
	v_max_f32_e32 v68, 0, v68
	v_max_f32_e32 v67, 0, v73
	v_max_f32_e32 v69, 0, v69
	v_pk_mul_f32 v[70:71], v[70:71], v[70:71]
	v_pk_mul_f32 v[72:73], v[66:67], v[66:67]
	v_pk_mul_f32 v[76:77], v[68:69], v[68:69]
	v_cvt_pk_bf16_f32 v66, v70, v71
	v_cvt_pk_bf16_f32 v67, v72, v73
	v_cvt_pk_bf16_f32 v68, v74, v75
	v_cvt_pk_bf16_f32 v69, v76, v77
	v_add_u32_e32 v70, 0x80, v140
	global_store_dwordx4 v[82:83], v[66:69], off offset:256
	v_ashrrev_i32_e32 v71, 31, v70
	s_and_b64 vcc, exec, s[6:7]
	v_mov_b32_e32 v66, 1.0
	v_mov_b32_e32 v68, 1.0
	s_cbranch_vccnz .LBB0_428
	v_mov_b32_e32 v67, v159
	v_fmamk_f32 v67, v67, 0x3a000000, v198
	v_mul_f32_e32 v68, 0x4b800000, v67
	v_cmp_gt_f32_e32 vcc, s16, v67
	s_nop 1
	v_cndmask_b32_e32 v67, v67, v68, vcc
	v_rsq_f32_e32 v67, v67
	s_nop 0
	v_mul_f32_e32 v68, 0x45800000, v67
	v_cndmask_b32_e32 v68, v67, v68, vcc
; __device__ __forceinline__ unsigned cvt_pk_bf16(float lo, float hi) { const cvt2_f32x2 v = {lo, hi}; const cvt2_bf16x2 r = __builtin_convertvector(v, cvt2_bf16x2); return __builtin_bit_cast(unsigned, r); }
;     __device__ __forceinline__ void operator()(const f32x4 (&acc)[2][2][4][2], const Unit& u, int wr, int wc, int fr, int fq) const {
;         const int row0 = u.pm * BM + wr * 64 + fr, col0 = u.pn * BM + wc * 32 + 8 * fq;
; #pragma unroll
;         for (int ai = 0; ai < 2; ++ai)
; #pragma unroll
;             for (int m = 0; m < 4; ++m) {
;                 const int row = row0 + ai * HALF + m * 16;
;                 const float rs = ssq ? rsqrtf(ssq[row] * (1.0f / 2048.0f) + RMS_EPS) : 1.0f;
;                 bf16_t* rowp = O + (size_t)row * ldc + col0;
; #pragma unroll
;                 for (int bj = 0; bj < 2; ++bj) {
;                     f32x4 v0 = acc[ai][bj][m][0] * rs, v1 = acc[ai][bj][m][1] * rs;
;                     if (RELU2) {
; #pragma unroll
;                         for (int e = 0; e < 4; ++e) { float a = fmaxf(v0[e], 0.f), b = fmaxf(v1[e], 0.f); v0[e] = a * a; v1[e] = b * b; }
;                     }
;                     u32x4 w; w.x = cvt_pk_bf16(v0[0], v0[1]); w.y = cvt_pk_bf16(v0[2], v0[3]); w.z = cvt_pk_bf16(v1[0], v1[1]); w.w = cvt_pk_bf16(v1[2], v1[3]);
;                     *(u32x4*)(rowp + bj * HALF) = w;
;                 }
.LBB0_428:
	v_pk_mul_f32 v[58:59], v[58:59], v[68:69] op_sel_hi:[1,0]
	v_pk_mul_f32 v[64:65], v[64:65], v[68:69] op_sel_hi:[1,0]
	v_pk_mul_f32 v[62:63], v[62:63], v[68:69] op_sel_hi:[1,0]
	v_pk_mul_f32 v[60:61], v[60:61], v[68:69] op_sel_hi:[1,0]
	v_max_f32_e32 v58, 0, v58
	v_max_f32_e32 v59, 0, v59
	v_lshlrev_b64 v[70:71], 14, v[70:71]
	v_max_f32_e32 v62, 0, v62
	v_max_f32_e32 v63, 0, v63
	v_pk_mul_f32 v[72:73], v[58:59], v[58:59]
	v_max_f32_e32 v58, 0, v64
	v_max_f32_e32 v60, 0, v60
	v_max_f32_e32 v59, 0, v65
	v_max_f32_e32 v61, 0, v61
	v_lshl_add_u64 v[70:71], s[30:31], 0, v[70:71]
	v_pk_mul_f32 v[62:63], v[62:63], v[62:63]
	v_pk_mul_f32 v[64:65], v[58:59], v[58:59]
	v_pk_mul_f32 v[74:75], v[60:61], v[60:61]
	v_pk_mul_f32 v[50:51], v[50:51], v[68:69] op_sel_hi:[1,0]
	v_lshl_add_u64 v[70:71], v[142:143], 1, v[70:71]
	v_cvt_pk_bf16_f32 v58, v62, v63
	v_cvt_pk_bf16_f32 v59, v64, v65
	v_cvt_pk_bf16_f32 v60, v72, v73
	v_cvt_pk_bf16_f32 v61, v74, v75
	v_pk_mul_f32 v[56:57], v[56:57], v[68:69] op_sel_hi:[1,0]
	v_pk_mul_f32 v[54:55], v[54:55], v[68:69] op_sel_hi:[1,0]
	v_pk_mul_f32 v[52:53], v[52:53], v[68:69] op_sel_hi:[1,0]
	v_max_f32_e32 v50, 0, v50
	v_max_f32_e32 v51, 0, v51
	global_store_dwordx4 v[70:71], v[58:61], off
	v_max_f32_e32 v54, 0, v54
	v_max_f32_e32 v55, 0, v55
	v_pk_mul_f32 v[58:59], v[50:51], v[50:51]
	v_max_f32_e32 v50, 0, v56
	v_max_f32_e32 v52, 0, v52
	v_max_f32_e32 v51, 0, v57
	v_max_f32_e32 v53, 0, v53
	v_pk_mul_f32 v[54:55], v[54:55], v[54:55]
	v_pk_mul_f32 v[56:57], v[50:51], v[50:51]
	v_pk_mul_f32 v[60:61], v[52:53], v[52:53]
	v_cvt_pk_bf16_f32 v50, v54, v55
	v_cvt_pk_bf16_f32 v51, v56, v57
	v_cvt_pk_bf16_f32 v52, v58, v59
	v_cvt_pk_bf16_f32 v53, v60, v61
	global_store_dwordx4 v[70:71], v[50:53], off offset:256
	s_and_b64 vcc, exec, s[6:7]
	s_nop 0
	v_add_u32_e32 v50, 0x90, v140
	v_ashrrev_i32_e32 v51, 31, v50
	s_cbranch_vccnz .LBB0_430
	v_mov_b32_e32 v52, v160
	v_fmamk_f32 v52, v52, 0x3a000000, v198
	v_mul_f32_e32 v53, 0x4b800000, v52
	v_cmp_gt_f32_e32 vcc, s16, v52
	s_nop 1
	v_cndmask_b32_e32 v52, v52, v53, vcc
	v_rsq_f32_e32 v52, v52
	s_nop 0
	v_mul_f32_e32 v53, 0x45800000, v52
	v_cndmask_b32_e32 v66, v52, v53, vcc
.LBB0_430:
	v_pk_mul_f32 v[42:43], v[42:43], v[66:67] op_sel_hi:[1,0]
	v_pk_mul_f32 v[48:49], v[48:49], v[66:67] op_sel_hi:[1,0]
	v_pk_mul_f32 v[46:47], v[46:47], v[66:67] op_sel_hi:[1,0]
	v_pk_mul_f32 v[44:45], v[44:45], v[66:67] op_sel_hi:[1,0]
	v_max_f32_e32 v42, 0, v42
	v_max_f32_e32 v43, 0, v43
	v_lshlrev_b64 v[50:51], 14, v[50:51]
	v_max_f32_e32 v46, 0, v46
	v_max_f32_e32 v47, 0, v47
	v_pk_mul_f32 v[52:53], v[42:43], v[42:43]
	v_max_f32_e32 v42, 0, v48
	v_max_f32_e32 v44, 0, v44
	v_max_f32_e32 v43, 0, v49
	v_max_f32_e32 v45, 0, v45
	v_lshl_add_u64 v[50:51], s[30:31], 0, v[50:51]
	v_pk_mul_f32 v[46:47], v[46:47], v[46:47]
	v_pk_mul_f32 v[48:49], v[42:43], v[42:43]
	v_pk_mul_f32 v[54:55], v[44:45], v[44:45]
	v_pk_mul_f32 v[34:35], v[34:35], v[66:67] op_sel_hi:[1,0]
	v_lshl_add_u64 v[50:51], v[142:143], 1, v[50:51]
	v_cvt_pk_bf16_f32 v42, v46, v47
	v_cvt_pk_bf16_f32 v43, v48, v49
	v_cvt_pk_bf16_f32 v44, v52, v53
	v_cvt_pk_bf16_f32 v45, v54, v55
	v_pk_mul_f32 v[40:41], v[40:41], v[66:67] op_sel_hi:[1,0]
	v_pk_mul_f32 v[38:39], v[38:39], v[66:67] op_sel_hi:[1,0]
	v_pk_mul_f32 v[36:37], v[36:37], v[66:67] op_sel_hi:[1,0]
	v_max_f32_e32 v34, 0, v34
	v_max_f32_e32 v35, 0, v35
	global_store_dwordx4 v[50:51], v[42:45], off
	v_max_f32_e32 v38, 0, v38
	v_max_f32_e32 v39, 0, v39
	v_pk_mul_f32 v[42:43], v[34:35], v[34:35]
	v_max_f32_e32 v34, 0, v40
	v_max_f32_e32 v36, 0, v36
	v_max_f32_e32 v35, 0, v41
	v_max_f32_e32 v37, 0, v37
	v_pk_mul_f32 v[38:39], v[38:39], v[38:39]
	v_pk_mul_f32 v[40:41], v[34:35], v[34:35]
	v_pk_mul_f32 v[44:45], v[36:37], v[36:37]
	v_cvt_pk_bf16_f32 v34, v38, v39
	v_cvt_pk_bf16_f32 v35, v40, v41
	v_cvt_pk_bf16_f32 v36, v42, v43
	v_cvt_pk_bf16_f32 v37, v44, v45
	v_add_u32_e32 v38, 0xa0, v140
	global_store_dwordx4 v[50:51], v[34:37], off offset:256
	v_ashrrev_i32_e32 v39, 31, v38
	s_and_b64 vcc, exec, s[6:7]
	v_mov_b32_e32 v34, 1.0
	v_mov_b32_e32 v36, 1.0
	s_cbranch_vccnz .LBB0_432
	v_mov_b32_e32 v35, v161
	v_fmamk_f32 v35, v35, 0x3a000000, v198
	v_mul_f32_e32 v36, 0x4b800000, v35
	v_cmp_gt_f32_e32 vcc, s16, v35
	s_nop 1
	v_cndmask_b32_e32 v35, v35, v36, vcc
	v_rsq_f32_e32 v35, v35
	s_nop 0
	v_mul_f32_e32 v36, 0x45800000, v35
	v_cndmask_b32_e32 v36, v35, v36, vcc
.LBB0_432:
	v_pk_mul_f32 v[26:27], v[26:27], v[36:37] op_sel_hi:[1,0]
	v_pk_mul_f32 v[32:33], v[32:33], v[36:37] op_sel_hi:[1,0]
	v_pk_mul_f32 v[30:31], v[30:31], v[36:37] op_sel_hi:[1,0]
	v_pk_mul_f32 v[28:29], v[28:29], v[36:37] op_sel_hi:[1,0]
	v_max_f32_e32 v26, 0, v26
	v_max_f32_e32 v27, 0, v27
	v_lshlrev_b64 v[38:39], 14, v[38:39]
	v_max_f32_e32 v30, 0, v30
	v_max_f32_e32 v31, 0, v31
	v_pk_mul_f32 v[40:41], v[26:27], v[26:27]
	v_max_f32_e32 v26, 0, v32
	v_max_f32_e32 v28, 0, v28
	v_max_f32_e32 v27, 0, v33
	v_max_f32_e32 v29, 0, v29
	v_lshl_add_u64 v[38:39], s[30:31], 0, v[38:39]
	v_pk_mul_f32 v[30:31], v[30:31], v[30:31]
	v_pk_mul_f32 v[32:33], v[26:27], v[26:27]
	v_pk_mul_f32 v[42:43], v[28:29], v[28:29]
	v_pk_mul_f32 v[18:19], v[18:19], v[36:37] op_sel_hi:[1,0]
	v_lshl_add_u64 v[38:39], v[142:143], 1, v[38:39]
	v_cvt_pk_bf16_f32 v26, v30, v31
	v_cvt_pk_bf16_f32 v27, v32, v33
	v_cvt_pk_bf16_f32 v28, v40, v41
	v_cvt_pk_bf16_f32 v29, v42, v43
	v_pk_mul_f32 v[24:25], v[24:25], v[36:37] op_sel_hi:[1,0]
	v_pk_mul_f32 v[22:23], v[22:23], v[36:37] op_sel_hi:[1,0]
	v_pk_mul_f32 v[20:21], v[20:21], v[36:37] op_sel_hi:[1,0]
	v_max_f32_e32 v18, 0, v18
	v_max_f32_e32 v19, 0, v19
	global_store_dwordx4 v[38:39], v[26:29], off
	v_max_f32_e32 v22, 0, v22
	v_max_f32_e32 v23, 0, v23
	v_pk_mul_f32 v[26:27], v[18:19], v[18:19]
	v_max_f32_e32 v18, 0, v24
	v_max_f32_e32 v20, 0, v20
	v_max_f32_e32 v19, 0, v25
	v_max_f32_e32 v21, 0, v21
	v_pk_mul_f32 v[22:23], v[22:23], v[22:23]
	v_pk_mul_f32 v[24:25], v[18:19], v[18:19]
	v_pk_mul_f32 v[28:29], v[20:21], v[20:21]
	v_cvt_pk_bf16_f32 v18, v22, v23
	v_cvt_pk_bf16_f32 v19, v24, v25
	v_cvt_pk_bf16_f32 v20, v26, v27
	v_cvt_pk_bf16_f32 v21, v28, v29
	global_store_dwordx4 v[38:39], v[18:21], off offset:256
	s_and_b64 vcc, exec, s[6:7]
	s_nop 0
	v_add_u32_e32 v18, 0xb0, v140
	v_ashrrev_i32_e32 v19, 31, v18
	s_cbranch_vccnz .LBB0_434
	v_mov_b32_e32 v20, v162
	v_fmamk_f32 v20, v20, 0x3a000000, v198
	v_mul_f32_e32 v21, 0x4b800000, v20
	v_cmp_gt_f32_e32 vcc, s16, v20
	s_nop 1
	v_cndmask_b32_e32 v20, v20, v21, vcc
	v_rsq_f32_e32 v20, v20
	s_nop 0
	v_mul_f32_e32 v21, 0x45800000, v20
	v_cndmask_b32_e32 v34, v20, v21, vcc
